# S5 step 3: C-matrix LDS image XOR-swizzled (16B chunk ^ row&3) so the 16 row-lanes of a ds_read_b128 no longer hit one bank group (16-way -> 4-way conflicts)
# baseline (speedup 1.0000x reference)
.LBB0_299:
	v_lshlrev_b32_e32 v101, 5, v130
	v_and_b32_e32 v101, 0xfffffe00, v101
	v_add3_u32 v100, 0, v101, v100
	v_and_b32_e32 v233, 0x30, v130
	v_xor_b32_e32 v100, v100, v233
	s_waitcnt lgkmcnt(0)
	s_barrier
	s_waitcnt vmcnt(8)
	ds_write_b128 v100, v[64:67] offset:256
	s_waitcnt vmcnt(7)
	ds_write_b128 v100, v[68:71] offset:16640
	s_waitcnt vmcnt(6)
	ds_write_b128 v100, v[72:75] offset:33024
	s_waitcnt vmcnt(5)
	ds_write_b128 v100, v[76:79] offset:49408
	v_add_u32_e32 v64, 0x10100, v100
	s_waitcnt vmcnt(4)
	ds_write_b128 v64, v[84:87]
	v_add_u32_e32 v64, 0x14100, v100
	s_waitcnt vmcnt(3)
	ds_write_b128 v64, v[80:83]
	v_add_u32_e32 v64, 0x18100, v100
	s_waitcnt vmcnt(2)
	ds_write_b128 v64, v[92:95]
	v_add_u32_e32 v64, 0x1c100, v100
	s_waitcnt vmcnt(1)
	ds_write_b128 v64, v[88:91]
	v_lshl_add_u32 v64, v130, 4, s19
	s_waitcnt vmcnt(0)
	ds_write_b128 v64, v[96:99]
	v_min_i32_e32 v64, 0, v182
	s_mov_b32 s0, 0x7fffff0
	v_mul_lo_u32 v64, v64, s0
	v_or_b32_e32 v64, v64, v128
	v_lshlrev_b32_e32 v64, 5, v64
	v_add3_u32 v64, s19, v64, v194
	s_waitcnt lgkmcnt(0)
	s_barrier
	ds_read_b128 v[64:67], v64
	v_add_u32_e32 v208, 0, v129
	v_and_b32_e32 v233, 3, v128
	v_lshlrev_b32_e32 v233, 4, v233
	v_xor_b32_e32 v232, v183, v233
	v_add_u32_e32 v156, v208, v232
	v_cmp_lt_i32_e64 s[0:1], 0, v182
	ds_read_b128 v[68:71], v156 offset:256
	v_add3_u32 v108, s10, v183, v129
	s_waitcnt lgkmcnt(1)
	v_cndmask_b32_e64 v67, v67, 0, s[0:1]
	v_cndmask_b32_e64 v66, v66, 0, s[0:1]
	v_cndmask_b32_e64 v65, v65, 0, s[0:1]
	v_cndmask_b32_e64 v64, v64, 0, s[0:1]
	ds_read_b128 v[92:95], v108
	ds_read_b128 v[84:87], v108 offset:64
	v_mfma_f32_16x16x32_bf16 v[72:75], v[64:67], v[0:3], 0
	ds_read_b128 v[88:91], v108 offset:8192
	ds_read_b128 v[80:83], v108 offset:8256
	ds_read_b128 v[96:99], v156 offset:320
	ds_read_b128 v[100:103], v156 offset:384
	v_mfma_f32_16x16x32_bf16 v[64:67], v[64:67], v[32:35], 0
	s_waitcnt lgkmcnt(5)
	v_mfma_f32_16x16x32_bf16 v[72:75], v[68:71], v[92:95], v[72:75]
	s_waitcnt lgkmcnt(3)
	v_mfma_f32_16x16x32_bf16 v[68:71], v[68:71], v[88:91], v[64:67]
	ds_read_b128 v[76:79], v108 offset:128
	s_nop 2
	ds_read_b128 v[64:67], v108 offset:192
	s_waitcnt lgkmcnt(3)
	v_mfma_f32_16x16x32_bf16 v[104:107], v[96:99], v[84:87], v[72:75]
	v_mfma_f32_16x16x32_bf16 v[96:99], v[96:99], v[80:83], v[68:71]
	s_nop 1
	ds_read_b128 v[72:75], v108 offset:8320
	ds_read_b128 v[68:71], v108 offset:8384
	ds_read_b128 v[116:119], v156 offset:448
	v_lshlrev_b32_e32 v108, 5, v128
	v_add3_u32 v194, s19, v108, v194
	s_waitcnt lgkmcnt(4)
	v_mfma_f32_16x16x32_bf16 v[104:107], v[100:103], v[76:79], v[104:107]
	v_sub_u32_e32 v108, 1, v182
	ds_read_b128 v[112:115], v156 offset:8448
	s_waitcnt lgkmcnt(3)
	v_mfma_f32_16x16x32_bf16 v[128:131], v[100:103], v[72:75], v[96:99]
	s_nop 2
	v_max_i32_e32 v96, 0, v108
	v_lshl_add_u32 v96, v96, 9, v194
	s_waitcnt lgkmcnt(1)
	v_mfma_f32_16x16x32_bf16 v[120:123], v[116:119], v[64:67], v[104:107]
	ds_read_b128 v[108:111], v156 offset:8512
	s_nop 1
	ds_read_b128 v[104:107], v156 offset:8576
	ds_read_b128 v[96:99], v96
	ds_read_b128 v[100:103], v156 offset:8640
	v_mfma_f32_16x16x32_bf16 v[116:119], v[116:119], v[68:71], v[128:131]
	s_nop 2
	v_mul_f32_e32 v128, 0x3f3504f3, v120
	v_cmp_nlt_f32_e64 s[8:9], |v128|, 1.0
	s_and_saveexec_b64 s[16:17], s[8:9]
	s_xor_b64 s[38:39], exec, s[16:17]
	s_cbranch_execz .LBB0_301
	v_fma_f32 v129, |v128|, s20, v222
	v_fma_f32 v129, |v128|, v129, s21
	v_fma_f32 v129, |v128|, v129, s22
	v_fma_f32 v129, |v128|, v129, s23
	v_fma_f32 v129, |v128|, v129, s24
	v_fma_f32 v129, |v128|, v129, s25
	v_fma_f32 v129, |v128|, v129, |v128|
	v_mul_f32_e32 v130, 0xbfb8aa3b, v129
	v_fma_f32 v131, v129, s26, -v130
	v_rndne_f32_e32 v132, v130
	v_fmac_f32_e32 v131, 0xb2a5705f, v129
	v_sub_f32_e32 v130, v130, v132
	v_add_f32_e32 v130, v130, v131
	v_cvt_i32_f32_e32 v131, v132
	v_exp_f32_e32 v130, v130
	v_cmp_nlt_f32_e32 vcc, s27, v129
	v_ldexp_f32 v130, v130, v131
	s_nop 0
	v_cndmask_b32_e32 v130, 0, v130, vcc
	v_cmp_ngt_f32_e32 vcc, s28, v129
	s_nop 1
	v_cndmask_b32_e32 v129, v223, v130, vcc
	v_sub_f32_e32 v129, 1.0, v129

.LBB0_521:
	s_andn2_saveexec_b64 s[0:1], s[0:1]
	v_mul_f32_e32 v120, v157, v157
	v_fmamk_f32 v121, v120, 0xba1345e1, v219
	v_fmaak_f32 v121, v120, v121, 0xbcdac9b8
	v_fmaak_f32 v121, v120, v121, 0x3de703be
	v_fmaak_f32 v121, v120, v121, 0xbec09330
	v_fmaak_f32 v120, v120, v121, 0x3e0375d0
	v_fma_f32 v159, |v157|, v120, |v157|
	s_or_b64 exec, exec, s[0:1]
	v_cmp_gt_i32_e32 vcc, 8, v182
	v_bfi_b32 v156, s29, v158, v156
	v_mul_f32_e32 v146, 0.5, v146
	s_waitcnt lgkmcnt(4)
	v_cndmask_b32_e32 v123, 0, v151, vcc
	v_cndmask_b32_e32 v122, 0, v150, vcc
	v_cndmask_b32_e32 v121, 0, v149, vcc
	v_cndmask_b32_e32 v120, 0, v148, vcc
	v_add_f32_e32 v156, 1.0, v156
	v_mul_f32_e32 v156, v146, v156
	v_mfma_f32_16x16x32_bf16 v[148:151], v[120:123], v[0:3], 0
	v_bfi_b32 v146, s29, v153, v152
	v_mul_f32_e32 v144, 0.5, v144
	v_add_f32_e32 v146, 1.0, v146
	v_mfma_f32_16x16x32_bf16 v[160:163], v[120:123], v[32:35], 0
	v_mul_f32_e32 v144, v144, v146
	v_bfi_b32 v146, s29, v155, v154
	v_mul_f32_e32 v145, 0.5, v145
	v_mfma_f32_16x16x32_bf16 v[148:151], v[112:115], v[4:7], v[148:151]
	v_add_f32_e32 v146, 1.0, v146
	v_mul_f32_e32 v145, v145, v146
	v_cvt_pk_bf16_f32 v152, v144, v145
	v_mfma_f32_16x16x32_bf16 v[160:163], v[112:115], v[36:39], v[160:163]
	v_bfi_b32 v145, s29, v159, v157
	v_mul_f32_e32 v144, 0.5, v147
	v_add_f32_e32 v145, 1.0, v145
	v_mfma_f32_16x16x32_bf16 v[148:151], v[100:103], v[8:11], v[148:151]
	v_mul_f32_e32 v153, v144, v145
	v_cvt_pk_bf16_f32 v153, v156, v153
	s_mov_b32 s0, 0x10100
	v_mfma_f32_16x16x32_bf16 v[160:163], v[100:103], v[40:43], v[160:163]
	v_mfma_f32_16x16x32_bf16 v[148:151], v[96:99], v[12:15], v[148:151]
	v_mfma_f32_16x16x32_bf16 v[160:163], v[96:99], v[44:47], v[160:163]
	s_waitcnt lgkmcnt(3)
	v_mfma_f32_16x16x32_bf16 v[148:151], v[140:143], v[92:95], v[148:151]
	v_mfma_f32_16x16x32_bf16 v[140:143], v[140:143], v[88:91], v[160:163]
	s_waitcnt lgkmcnt(2)
	v_mfma_f32_16x16x32_bf16 v[144:147], v[136:139], v[84:87], v[148:151]
	s_nop 2
	v_add3_u32 v160, v208, v232, s0
	s_nop 0
	v_lshl_add_u64 v[148:149], v[186:187], 0, s[92:93]
	v_lshl_add_u64 v[148:149], v[180:181], 1, v[148:149]
	v_mfma_f32_16x16x32_bf16 v[136:139], v[136:139], v[80:83], v[140:143]
	s_nop 2
	v_add_co_u32_e32 v140, vcc, s60, v148
	s_waitcnt lgkmcnt(1)
	v_mfma_f32_16x16x32_bf16 v[162:165], v[128:131], v[72:75], v[136:139]
	v_addc_co_u32_e32 v141, vcc, 0, v149, vcc
	global_store_dwordx2 v[140:141], v[152:153], off offset:2048
	v_sub_u32_e32 v140, 8, v182
	v_mfma_f32_16x16x32_bf16 v[148:151], v[128:131], v[76:79], v[144:147]
	v_max_i32_e32 v140, 0, v140
	v_lshl_add_u32 v140, v140, 9, v194
	ds_read_b128 v[152:155], v140
	ds_read_b128 v[144:147], v160
	ds_read_b128 v[140:143], v160 offset:64
	ds_read_b128 v[136:139], v160 offset:128
	s_waitcnt lgkmcnt(4)
	v_mfma_f32_16x16x32_bf16 v[156:159], v[132:135], v[64:67], v[148:151]
	ds_read_b128 v[128:131], v160 offset:192
	v_mfma_f32_16x16x32_bf16 v[148:151], v[132:135], v[68:71], v[162:165]
	s_nop 5
	v_mul_f32_e32 v160, 0x3f3504f3, v156
	v_cmp_nlt_f32_e64 s[0:1], |v160|, 1.0
	s_and_saveexec_b64 s[8:9], s[0:1]
	s_xor_b64 s[0:1], exec, s[8:9]
	s_cbranch_execz .LBB0_525
	v_fma_f32 v132, |v160|, s20, v222
	v_fma_f32 v132, |v160|, v132, s21
	v_fma_f32 v132, |v160|, v132, s22
	v_fma_f32 v132, |v160|, v132, s23
	v_fma_f32 v132, |v160|, v132, s24
	v_fma_f32 v132, |v160|, v132, s25
	v_fma_f32 v132, |v160|, v132, |v160|
	v_mul_f32_e32 v133, 0xbfb8aa3b, v132
	v_fma_f32 v134, v132, s26, -v133
	v_rndne_f32_e32 v135, v133
	v_fmac_f32_e32 v134, 0xb2a5705f, v132
	v_sub_f32_e32 v133, v133, v135
	v_add_f32_e32 v133, v133, v134
	v_cvt_i32_f32_e32 v134, v135
	v_exp_f32_e32 v133, v133
	v_cmp_nlt_f32_e32 vcc, s27, v132
	v_ldexp_f32 v133, v133, v134
	s_nop 0
	v_cndmask_b32_e32 v133, 0, v133, vcc
	v_cmp_ngt_f32_e32 vcc, s28, v132
	s_nop 1
	v_cndmask_b32_e32 v132, v223, v133, vcc
	v_sub_f32_e32 v161, 1.0, v132

.LBB0_553:
	s_andn2_saveexec_b64 s[0:1], s[0:1]
	v_mul_f32_e32 v132, v161, v161
	v_fmamk_f32 v133, v132, 0xba1345e1, v219
	v_fmaak_f32 v133, v132, v133, 0xbcdac9b8
	v_fmaak_f32 v133, v132, v133, 0x3de703be
	v_fmaak_f32 v133, v132, v133, 0xbec09330
	v_fmaak_f32 v132, v132, v133, 0x3e0375d0
	v_fma_f32 v163, |v161|, v132, |v161|
	s_or_b64 exec, exec, s[0:1]
	v_cmp_gt_i32_e32 vcc, 9, v182
	v_bfi_b32 v160, s29, v162, v160
	v_mul_f32_e32 v150, 0.5, v150
	s_waitcnt lgkmcnt(4)
	v_cndmask_b32_e32 v135, 0, v155, vcc
	v_cndmask_b32_e32 v134, 0, v154, vcc
	v_cndmask_b32_e32 v133, 0, v153, vcc
	v_cndmask_b32_e32 v132, 0, v152, vcc
	v_add_f32_e32 v160, 1.0, v160
	v_mul_f32_e32 v160, v150, v160
	v_mfma_f32_16x16x32_bf16 v[152:155], v[132:135], v[0:3], 0
	v_bfi_b32 v150, s29, v157, v156
	v_mul_f32_e32 v148, 0.5, v148
	v_add_f32_e32 v150, 1.0, v150
	v_mfma_f32_16x16x32_bf16 v[164:167], v[132:135], v[32:35], 0
	v_mul_f32_e32 v148, v148, v150
	v_bfi_b32 v150, s29, v159, v158
	v_mul_f32_e32 v149, 0.5, v149
	v_mfma_f32_16x16x32_bf16 v[152:155], v[124:127], v[4:7], v[152:155]
	v_add_f32_e32 v150, 1.0, v150
	v_mul_f32_e32 v149, v149, v150
	v_cvt_pk_bf16_f32 v156, v148, v149
	v_mfma_f32_16x16x32_bf16 v[164:167], v[124:127], v[36:39], v[164:167]
	v_bfi_b32 v149, s29, v163, v161
	v_mul_f32_e32 v148, 0.5, v151
	v_add_f32_e32 v149, 1.0, v149
	v_mfma_f32_16x16x32_bf16 v[152:155], v[116:119], v[8:11], v[152:155]
	v_mul_f32_e32 v157, v148, v149
	s_mov_b32 s0, 0x14000
	v_cvt_pk_bf16_f32 v157, v160, v157
	v_mfma_f32_16x16x32_bf16 v[164:167], v[116:119], v[40:43], v[164:167]
	v_mfma_f32_16x16x32_bf16 v[152:155], v[108:111], v[12:15], v[152:155]
	v_mfma_f32_16x16x32_bf16 v[164:167], v[108:111], v[44:47], v[164:167]
	v_mfma_f32_16x16x32_bf16 v[152:155], v[104:107], v[16:19], v[152:155]
	v_mfma_f32_16x16x32_bf16 v[164:167], v[104:107], v[48:51], v[164:167]
	s_waitcnt lgkmcnt(3)
	v_mfma_f32_16x16x32_bf16 v[152:155], v[144:147], v[92:95], v[152:155]
	v_mfma_f32_16x16x32_bf16 v[144:147], v[144:147], v[88:91], v[164:167]
	s_waitcnt lgkmcnt(2)
	v_mfma_f32_16x16x32_bf16 v[148:151], v[140:143], v[84:87], v[152:155]
	s_nop 4
	v_lshl_add_u64 v[152:153], v[186:187], 0, s[92:93]
	v_lshl_add_u64 v[152:153], v[180:181], 1, v[152:153]
	v_mfma_f32_16x16x32_bf16 v[140:143], v[140:143], v[80:83], v[144:147]
	s_nop 2
	v_add_co_u32_e32 v144, vcc, s0, v152
	s_mov_b32 s0, 0x12100
	s_nop 0
	v_addc_co_u32_e32 v145, vcc, 0, v153, vcc
	global_store_dwordx2 v[144:145], v[156:157], off offset:1024
	v_sub_u32_e32 v144, 9, v182
	s_waitcnt lgkmcnt(1)
	v_mfma_f32_16x16x32_bf16 v[152:155], v[136:139], v[76:79], v[148:151]
	v_max_i32_e32 v144, 0, v144
	v_lshl_add_u32 v144, v144, 9, v194
	v_add3_u32 v164, v208, v232, s0
	v_mfma_f32_16x16x32_bf16 v[166:169], v[136:139], v[72:75], v[140:143]
	ds_read_b128 v[156:159], v144
	ds_read_b128 v[148:151], v164
	ds_read_b128 v[144:147], v164 offset:64
	ds_read_b128 v[136:139], v164 offset:128
	ds_read_b128 v[140:143], v164 offset:192
	s_waitcnt lgkmcnt(5)
	v_mfma_f32_16x16x32_bf16 v[160:163], v[128:131], v[64:67], v[152:155]
	v_mfma_f32_16x16x32_bf16 v[152:155], v[128:131], v[68:71], v[166:169]
	s_nop 6
	v_mul_f32_e32 v164, 0x3f3504f3, v160
	v_cmp_nlt_f32_e64 s[0:1], |v164|, 1.0
	s_and_saveexec_b64 s[8:9], s[0:1]
	s_xor_b64 s[0:1], exec, s[8:9]
	s_cbranch_execz .LBB0_557
	v_fma_f32 v128, |v164|, s20, v222
	v_fma_f32 v128, |v164|, v128, s21
	v_fma_f32 v128, |v164|, v128, s22
	v_fma_f32 v128, |v164|, v128, s23
	v_fma_f32 v128, |v164|, v128, s24
	v_fma_f32 v128, |v164|, v128, s25
	v_fma_f32 v128, |v164|, v128, |v164|
	v_mul_f32_e32 v129, 0xbfb8aa3b, v128
	v_fma_f32 v130, v128, s26, -v129
	v_rndne_f32_e32 v131, v129
	v_fmac_f32_e32 v130, 0xb2a5705f, v128
	v_sub_f32_e32 v129, v129, v131
	v_add_f32_e32 v129, v129, v130
	v_cvt_i32_f32_e32 v130, v131
	v_exp_f32_e32 v129, v129
	v_cmp_nlt_f32_e32 vcc, s27, v128
	v_ldexp_f32 v129, v129, v130
	s_nop 0
	v_cndmask_b32_e32 v129, 0, v129, vcc
	v_cmp_ngt_f32_e32 vcc, s28, v128
	s_nop 1
	v_cndmask_b32_e32 v128, v223, v129, vcc
	v_sub_f32_e32 v165, 1.0, v128

.LBB0_585:
	s_andn2_saveexec_b64 s[0:1], s[0:1]
	v_mul_f32_e32 v128, v165, v165
	v_fmamk_f32 v129, v128, 0xba1345e1, v219
	v_fmaak_f32 v129, v128, v129, 0xbcdac9b8
	v_fmaak_f32 v129, v128, v129, 0x3de703be
	v_fmaak_f32 v129, v128, v129, 0xbec09330
	v_fmaak_f32 v128, v128, v129, 0x3e0375d0
	v_fma_f32 v167, |v165|, v128, |v165|
	s_or_b64 exec, exec, s[0:1]
	v_cmp_gt_i32_e32 vcc, 10, v182
	v_bfi_b32 v164, s29, v166, v164
	v_mul_f32_e32 v154, 0.5, v154
	s_waitcnt lgkmcnt(4)
	v_cndmask_b32_e32 v131, 0, v159, vcc
	v_cndmask_b32_e32 v130, 0, v158, vcc
	v_cndmask_b32_e32 v129, 0, v157, vcc
	v_cndmask_b32_e32 v128, 0, v156, vcc
	v_add_f32_e32 v164, 1.0, v164
	v_mul_f32_e32 v164, v154, v164
	v_mfma_f32_16x16x32_bf16 v[156:159], v[128:131], v[0:3], 0
	v_bfi_b32 v154, s29, v161, v160
	v_mul_f32_e32 v152, 0.5, v152
	v_add_f32_e32 v154, 1.0, v154
	v_mfma_f32_16x16x32_bf16 v[168:171], v[128:131], v[32:35], 0
	v_mul_f32_e32 v152, v152, v154
	v_bfi_b32 v154, s29, v163, v162
	v_mul_f32_e32 v153, 0.5, v153
	v_mfma_f32_16x16x32_bf16 v[156:159], v[120:123], v[4:7], v[156:159]
	v_add_f32_e32 v154, 1.0, v154
	v_mul_f32_e32 v153, v153, v154
	v_cvt_pk_bf16_f32 v160, v152, v153
	v_mfma_f32_16x16x32_bf16 v[168:171], v[120:123], v[36:39], v[168:171]
	v_bfi_b32 v153, s29, v167, v165
	v_mul_f32_e32 v152, 0.5, v155
	v_add_f32_e32 v153, 1.0, v153
	v_mfma_f32_16x16x32_bf16 v[156:159], v[112:115], v[8:11], v[156:159]
	v_mul_f32_e32 v161, v152, v153
	v_cvt_pk_bf16_f32 v161, v164, v161
	s_mov_b32 s0, 0x14100
	v_mfma_f32_16x16x32_bf16 v[168:171], v[112:115], v[40:43], v[168:171]
	v_mfma_f32_16x16x32_bf16 v[156:159], v[100:103], v[12:15], v[156:159]
	v_mfma_f32_16x16x32_bf16 v[168:171], v[100:103], v[44:47], v[168:171]
	v_mfma_f32_16x16x32_bf16 v[156:159], v[96:99], v[16:19], v[156:159]
	v_mfma_f32_16x16x32_bf16 v[168:171], v[96:99], v[48:51], v[168:171]
	s_waitcnt lgkmcnt(3)
	v_mfma_f32_16x16x32_bf16 v[156:159], v[148:151], v[92:95], v[156:159]
	v_mfma_f32_16x16x32_bf16 v[148:151], v[148:151], v[88:91], v[168:171]
	s_waitcnt lgkmcnt(2)
	v_mfma_f32_16x16x32_bf16 v[152:155], v[144:147], v[84:87], v[156:159]
	s_nop 2
	v_add3_u32 v168, v208, v232, s0
	s_nop 0
	v_lshl_add_u64 v[156:157], v[186:187], 0, s[92:93]
	v_lshl_add_u64 v[156:157], v[180:181], 1, v[156:157]
	v_mfma_f32_16x16x32_bf16 v[144:147], v[144:147], v[80:83], v[148:151]
	s_nop 2
	v_add_co_u32_e32 v148, vcc, s64, v156
	s_waitcnt lgkmcnt(1)
	v_mfma_f32_16x16x32_bf16 v[170:173], v[136:139], v[72:75], v[144:147]
	v_addc_co_u32_e32 v149, vcc, 0, v157, vcc
	global_store_dwordx2 v[148:149], v[160:161], off
	v_sub_u32_e32 v148, 10, v182
	v_mfma_f32_16x16x32_bf16 v[156:159], v[136:139], v[76:79], v[152:155]
	v_max_i32_e32 v148, 0, v148
	v_lshl_add_u32 v148, v148, 9, v194
	ds_read_b128 v[160:163], v148
	ds_read_b128 v[152:155], v168
	ds_read_b128 v[148:151], v168 offset:64
	ds_read_b128 v[144:147], v168 offset:128
	s_waitcnt lgkmcnt(4)
	v_mfma_f32_16x16x32_bf16 v[164:167], v[140:143], v[64:67], v[156:159]
	ds_read_b128 v[136:139], v168 offset:192
	v_mfma_f32_16x16x32_bf16 v[156:159], v[140:143], v[68:71], v[170:173]
	s_nop 5
	v_mul_f32_e32 v168, 0x3f3504f3, v164
	v_cmp_nlt_f32_e64 s[0:1], |v168|, 1.0
	s_and_saveexec_b64 s[8:9], s[0:1]
	s_xor_b64 s[0:1], exec, s[8:9]
	s_cbranch_execz .LBB0_589
	v_fma_f32 v140, |v168|, s20, v222
	v_fma_f32 v140, |v168|, v140, s21
	v_fma_f32 v140, |v168|, v140, s22
	v_fma_f32 v140, |v168|, v140, s23
	v_fma_f32 v140, |v168|, v140, s24
	v_fma_f32 v140, |v168|, v140, s25
	v_fma_f32 v140, |v168|, v140, |v168|
	v_mul_f32_e32 v141, 0xbfb8aa3b, v140
	v_fma_f32 v142, v140, s26, -v141
	v_rndne_f32_e32 v143, v141
	v_fmac_f32_e32 v142, 0xb2a5705f, v140
	v_sub_f32_e32 v141, v141, v143
	v_add_f32_e32 v141, v141, v142
	v_cvt_i32_f32_e32 v142, v143
	v_exp_f32_e32 v141, v141
	v_cmp_nlt_f32_e32 vcc, s27, v140
	v_ldexp_f32 v141, v141, v142
	s_nop 0
	v_cndmask_b32_e32 v141, 0, v141, vcc
	v_cmp_ngt_f32_e32 vcc, s28, v140
	s_nop 1
	v_cndmask_b32_e32 v140, v223, v141, vcc
	v_sub_f32_e32 v169, 1.0, v140

.LBB0_617:
	s_andn2_saveexec_b64 s[0:1], s[0:1]
	v_mul_f32_e32 v140, v169, v169
	v_fmamk_f32 v141, v140, 0xba1345e1, v219
	v_fmaak_f32 v141, v140, v141, 0xbcdac9b8
	v_fmaak_f32 v141, v140, v141, 0x3de703be
	v_fmaak_f32 v141, v140, v141, 0xbec09330
	v_fmaak_f32 v140, v140, v141, 0x3e0375d0
	v_fma_f32 v171, |v169|, v140, |v169|
	s_or_b64 exec, exec, s[0:1]
	v_cmp_gt_i32_e32 vcc, 11, v182
	v_bfi_b32 v168, s29, v170, v168
	v_mul_f32_e32 v158, 0.5, v158
	s_waitcnt lgkmcnt(4)
	v_cndmask_b32_e32 v143, 0, v163, vcc
	v_cndmask_b32_e32 v142, 0, v162, vcc
	v_cndmask_b32_e32 v141, 0, v161, vcc
	v_cndmask_b32_e32 v140, 0, v160, vcc
	v_add_f32_e32 v168, 1.0, v168
	v_mul_f32_e32 v168, v158, v168
	v_mfma_f32_16x16x32_bf16 v[160:163], v[140:143], v[0:3], 0
	v_bfi_b32 v158, s29, v165, v164
	v_mul_f32_e32 v156, 0.5, v156
	v_add_f32_e32 v158, 1.0, v158
	v_mfma_f32_16x16x32_bf16 v[172:175], v[140:143], v[32:35], 0
	v_mul_f32_e32 v156, v156, v158
	v_bfi_b32 v158, s29, v167, v166
	v_mul_f32_e32 v157, 0.5, v157
	v_mfma_f32_16x16x32_bf16 v[160:163], v[132:135], v[4:7], v[160:163]
	v_add_f32_e32 v158, 1.0, v158
	v_mul_f32_e32 v157, v157, v158
	v_cvt_pk_bf16_f32 v164, v156, v157
	v_mfma_f32_16x16x32_bf16 v[172:175], v[132:135], v[36:39], v[172:175]
	v_bfi_b32 v157, s29, v171, v169
	v_mul_f32_e32 v156, 0.5, v159
	v_add_f32_e32 v157, 1.0, v157
	v_mfma_f32_16x16x32_bf16 v[160:163], v[124:127], v[8:11], v[160:163]
	v_mul_f32_e32 v165, v156, v157
	s_mov_b32 s0, 0x19000
	v_cvt_pk_bf16_f32 v165, v168, v165
	v_mfma_f32_16x16x32_bf16 v[172:175], v[124:127], v[40:43], v[172:175]
	v_mfma_f32_16x16x32_bf16 v[160:163], v[116:119], v[12:15], v[160:163]
	v_mfma_f32_16x16x32_bf16 v[172:175], v[116:119], v[44:47], v[172:175]
	v_mfma_f32_16x16x32_bf16 v[160:163], v[108:111], v[16:19], v[160:163]
	v_mfma_f32_16x16x32_bf16 v[172:175], v[108:111], v[48:51], v[172:175]
	v_mfma_f32_16x16x32_bf16 v[160:163], v[104:107], v[20:23], v[160:163]
	v_mfma_f32_16x16x32_bf16 v[172:175], v[104:107], v[52:55], v[172:175]
	s_waitcnt lgkmcnt(3)
	v_mfma_f32_16x16x32_bf16 v[160:163], v[152:155], v[92:95], v[160:163]
	v_mfma_f32_16x16x32_bf16 v[152:155], v[152:155], v[88:91], v[172:175]
	s_waitcnt lgkmcnt(2)
	v_mfma_f32_16x16x32_bf16 v[156:159], v[148:151], v[84:87], v[160:163]
	s_nop 4
	v_lshl_add_u64 v[160:161], v[186:187], 0, s[92:93]
	v_lshl_add_u64 v[160:161], v[180:181], 1, v[160:161]
	v_mfma_f32_16x16x32_bf16 v[148:151], v[148:151], v[80:83], v[152:155]
	s_nop 2
	v_add_co_u32_e32 v152, vcc, s0, v160
	s_mov_b32 s0, 0x16100
	s_nop 0
	v_addc_co_u32_e32 v153, vcc, 0, v161, vcc
	global_store_dwordx2 v[152:153], v[164:165], off offset:3072
	v_sub_u32_e32 v152, 11, v182
	s_waitcnt lgkmcnt(1)
	v_mfma_f32_16x16x32_bf16 v[160:163], v[144:147], v[76:79], v[156:159]
	v_max_i32_e32 v152, 0, v152
	v_lshl_add_u32 v152, v152, 9, v194
	v_add3_u32 v172, v208, v232, s0
	v_mfma_f32_16x16x32_bf16 v[174:177], v[144:147], v[72:75], v[148:151]
	ds_read_b128 v[164:167], v152
	ds_read_b128 v[156:159], v172
	ds_read_b128 v[152:155], v172 offset:64
	ds_read_b128 v[144:147], v172 offset:128
	ds_read_b128 v[148:151], v172 offset:192
	s_waitcnt lgkmcnt(5)
	v_mfma_f32_16x16x32_bf16 v[168:171], v[136:139], v[64:67], v[160:163]
	v_mfma_f32_16x16x32_bf16 v[160:163], v[136:139], v[68:71], v[174:177]
	s_nop 6
	v_mul_f32_e32 v172, 0x3f3504f3, v168
	v_cmp_nlt_f32_e64 s[0:1], |v172|, 1.0
	s_and_saveexec_b64 s[8:9], s[0:1]
	s_xor_b64 s[0:1], exec, s[8:9]
	s_cbranch_execz .LBB0_621
	v_fma_f32 v136, |v172|, s20, v222
	v_fma_f32 v136, |v172|, v136, s21
	v_fma_f32 v136, |v172|, v136, s22
	v_fma_f32 v136, |v172|, v136, s23
	v_fma_f32 v136, |v172|, v136, s24
	v_fma_f32 v136, |v172|, v136, s25
	v_fma_f32 v136, |v172|, v136, |v172|
	v_mul_f32_e32 v137, 0xbfb8aa3b, v136
	v_fma_f32 v138, v136, s26, -v137
	v_rndne_f32_e32 v139, v137
	v_fmac_f32_e32 v138, 0xb2a5705f, v136
	v_sub_f32_e32 v137, v137, v139
	v_add_f32_e32 v137, v137, v138
	v_cvt_i32_f32_e32 v138, v139
	v_exp_f32_e32 v137, v137
	v_cmp_nlt_f32_e32 vcc, s27, v136
	v_ldexp_f32 v137, v137, v138
	s_nop 0
	v_cndmask_b32_e32 v137, 0, v137, vcc
	v_cmp_ngt_f32_e32 vcc, s28, v136
	s_nop 1
	v_cndmask_b32_e32 v136, v223, v137, vcc
	v_sub_f32_e32 v173, 1.0, v136

.LBB0_649:
	s_andn2_saveexec_b64 s[0:1], s[0:1]
	v_mul_f32_e32 v136, v173, v173
	v_fmamk_f32 v137, v136, 0xba1345e1, v219
	v_fmaak_f32 v137, v136, v137, 0xbcdac9b8
	v_fmaak_f32 v137, v136, v137, 0x3de703be
	v_fmaak_f32 v137, v136, v137, 0xbec09330
	v_fmaak_f32 v136, v136, v137, 0x3e0375d0
	v_fma_f32 v175, |v173|, v136, |v173|
	s_or_b64 exec, exec, s[0:1]
	v_cmp_gt_i32_e32 vcc, 12, v182
	v_bfi_b32 v172, s29, v174, v172
	v_mul_f32_e32 v162, 0.5, v162
	s_waitcnt lgkmcnt(4)
	v_cndmask_b32_e32 v139, 0, v167, vcc
	v_cndmask_b32_e32 v138, 0, v166, vcc
	v_cndmask_b32_e32 v137, 0, v165, vcc
	v_cndmask_b32_e32 v136, 0, v164, vcc
	v_add_f32_e32 v172, 1.0, v172
	v_mul_f32_e32 v172, v162, v172
	v_mfma_f32_16x16x32_bf16 v[164:167], v[136:139], v[0:3], 0
	v_bfi_b32 v162, s29, v169, v168
	v_mul_f32_e32 v160, 0.5, v160
	v_add_f32_e32 v162, 1.0, v162
	v_mfma_f32_16x16x32_bf16 v[176:179], v[136:139], v[32:35], 0
	v_mul_f32_e32 v160, v160, v162
	v_bfi_b32 v162, s29, v171, v170
	v_mul_f32_e32 v161, 0.5, v161
	v_mfma_f32_16x16x32_bf16 v[164:167], v[128:131], v[4:7], v[164:167]
	v_add_f32_e32 v162, 1.0, v162
	v_mul_f32_e32 v161, v161, v162
	v_cvt_pk_bf16_f32 v168, v160, v161
	v_mfma_f32_16x16x32_bf16 v[176:179], v[128:131], v[36:39], v[176:179]
	v_bfi_b32 v161, s29, v175, v173
	v_mul_f32_e32 v160, 0.5, v163
	v_add_f32_e32 v161, 1.0, v161
	v_mfma_f32_16x16x32_bf16 v[164:167], v[120:123], v[8:11], v[164:167]
	v_mul_f32_e32 v169, v160, v161
	v_cvt_pk_bf16_f32 v169, v172, v169
	s_mov_b32 s0, 0x18100
	v_mfma_f32_16x16x32_bf16 v[176:179], v[120:123], v[40:43], v[176:179]
	v_mfma_f32_16x16x32_bf16 v[164:167], v[112:115], v[12:15], v[164:167]
	v_mfma_f32_16x16x32_bf16 v[176:179], v[112:115], v[44:47], v[176:179]
	v_mfma_f32_16x16x32_bf16 v[164:167], v[100:103], v[16:19], v[164:167]
	v_mfma_f32_16x16x32_bf16 v[176:179], v[100:103], v[48:51], v[176:179]
	v_mfma_f32_16x16x32_bf16 v[164:167], v[96:99], v[20:23], v[164:167]
	v_mfma_f32_16x16x32_bf16 v[176:179], v[96:99], v[52:55], v[176:179]
	s_waitcnt lgkmcnt(3)
	v_mfma_f32_16x16x32_bf16 v[164:167], v[156:159], v[92:95], v[164:167]
	v_mfma_f32_16x16x32_bf16 v[156:159], v[156:159], v[88:91], v[176:179]
	s_waitcnt lgkmcnt(2)
	v_mfma_f32_16x16x32_bf16 v[160:163], v[152:155], v[84:87], v[164:167]
	s_nop 2
	v_add3_u32 v176, v208, v232, s0
	s_nop 0
	v_lshl_add_u64 v[164:165], v[186:187], 0, s[92:93]
	v_lshl_add_u64 v[164:165], v[180:181], 1, v[164:165]
	v_mfma_f32_16x16x32_bf16 v[152:155], v[152:155], v[80:83], v[156:159]
	s_nop 2
	v_add_co_u32_e32 v156, vcc, s46, v164
	s_waitcnt lgkmcnt(1)
	v_mfma_f32_16x16x32_bf16 v[210:213], v[144:147], v[72:75], v[152:155]
	v_addc_co_u32_e32 v157, vcc, 0, v165, vcc
	global_store_dwordx2 v[156:157], v[168:169], off offset:2048
	v_sub_u32_e32 v156, 12, v182
	v_mfma_f32_16x16x32_bf16 v[164:167], v[144:147], v[76:79], v[160:163]
	v_max_i32_e32 v156, 0, v156
	v_lshl_add_u32 v156, v156, 9, v194
	ds_read_b128 v[168:171], v156
	ds_read_b128 v[160:163], v176
	ds_read_b128 v[156:159], v176 offset:64
	ds_read_b128 v[152:155], v176 offset:128
	s_waitcnt lgkmcnt(4)
	v_mfma_f32_16x16x32_bf16 v[172:175], v[148:151], v[64:67], v[164:167]
	ds_read_b128 v[144:147], v176 offset:192
	v_mfma_f32_16x16x32_bf16 v[164:167], v[148:151], v[68:71], v[210:213]
	s_nop 5
	v_mul_f32_e32 v176, 0x3f3504f3, v172
	v_cmp_nlt_f32_e64 s[0:1], |v176|, 1.0
	s_and_saveexec_b64 s[8:9], s[0:1]
	s_xor_b64 s[0:1], exec, s[8:9]
	s_cbranch_execz .LBB0_653
	v_fma_f32 v148, |v176|, s20, v222
	v_fma_f32 v148, |v176|, v148, s21
	v_fma_f32 v148, |v176|, v148, s22
	v_fma_f32 v148, |v176|, v148, s23
	v_fma_f32 v148, |v176|, v148, s24
	v_fma_f32 v148, |v176|, v148, s25
	v_fma_f32 v148, |v176|, v148, |v176|
	v_mul_f32_e32 v149, 0xbfb8aa3b, v148
	v_fma_f32 v150, v148, s26, -v149
	v_rndne_f32_e32 v151, v149
	v_fmac_f32_e32 v150, 0xb2a5705f, v148
	v_sub_f32_e32 v149, v149, v151
	v_add_f32_e32 v149, v149, v150
	v_cvt_i32_f32_e32 v150, v151
	v_exp_f32_e32 v149, v149
	v_cmp_nlt_f32_e32 vcc, s27, v148
	v_ldexp_f32 v149, v149, v150
	s_nop 0
	v_cndmask_b32_e32 v149, 0, v149, vcc
	v_cmp_ngt_f32_e32 vcc, s28, v148
	s_nop 1
	v_cndmask_b32_e32 v148, v223, v149, vcc
	v_sub_f32_e32 v177, 1.0, v148

.LBB0_681:
	s_andn2_saveexec_b64 s[0:1], s[0:1]
	v_mul_f32_e32 v148, v177, v177
	v_fmamk_f32 v149, v148, 0xba1345e1, v219
	v_fmaak_f32 v149, v148, v149, 0xbcdac9b8
	v_fmaak_f32 v149, v148, v149, 0x3de703be
	v_fmaak_f32 v149, v148, v149, 0xbec09330
	v_fmaak_f32 v148, v148, v149, 0x3e0375d0
	v_fma_f32 v179, |v177|, v148, |v177|
	s_or_b64 exec, exec, s[0:1]
	v_cmp_gt_i32_e32 vcc, 13, v182
	v_bfi_b32 v176, s29, v178, v176
	v_mul_f32_e32 v166, 0.5, v166
	s_waitcnt lgkmcnt(4)
	v_cndmask_b32_e32 v151, 0, v171, vcc
	v_cndmask_b32_e32 v150, 0, v170, vcc
	v_cndmask_b32_e32 v149, 0, v169, vcc
	v_cndmask_b32_e32 v148, 0, v168, vcc
	v_add_f32_e32 v176, 1.0, v176
	v_mul_f32_e32 v176, v166, v176
	v_mfma_f32_16x16x32_bf16 v[168:171], v[148:151], v[0:3], 0
	v_bfi_b32 v166, s29, v173, v172
	v_mul_f32_e32 v164, 0.5, v164
	v_add_f32_e32 v166, 1.0, v166
	v_mfma_f32_16x16x32_bf16 v[210:213], v[148:151], v[32:35], 0
	v_mul_f32_e32 v164, v164, v166
	v_bfi_b32 v166, s29, v175, v174
	v_mul_f32_e32 v165, 0.5, v165
	v_mfma_f32_16x16x32_bf16 v[168:171], v[140:143], v[4:7], v[168:171]
	v_add_f32_e32 v166, 1.0, v166
	v_mul_f32_e32 v165, v165, v166
	v_cvt_pk_bf16_f32 v172, v164, v165
	v_mfma_f32_16x16x32_bf16 v[210:213], v[140:143], v[36:39], v[210:213]
	v_bfi_b32 v165, s29, v179, v177
	v_mul_f32_e32 v164, 0.5, v167
	v_add_f32_e32 v165, 1.0, v165
	v_mfma_f32_16x16x32_bf16 v[168:171], v[132:135], v[8:11], v[168:171]
	v_mul_f32_e32 v173, v164, v165
	s_mov_b32 s0, 0x1f000
	v_cvt_pk_bf16_f32 v173, v176, v173
	v_mfma_f32_16x16x32_bf16 v[210:213], v[132:135], v[40:43], v[210:213]
	v_mfma_f32_16x16x32_bf16 v[168:171], v[124:127], v[12:15], v[168:171]
	v_mfma_f32_16x16x32_bf16 v[210:213], v[124:127], v[44:47], v[210:213]
	v_mfma_f32_16x16x32_bf16 v[168:171], v[116:119], v[16:19], v[168:171]
	v_mfma_f32_16x16x32_bf16 v[210:213], v[116:119], v[48:51], v[210:213]
	v_mfma_f32_16x16x32_bf16 v[168:171], v[108:111], v[20:23], v[168:171]
	v_mfma_f32_16x16x32_bf16 v[210:213], v[108:111], v[52:55], v[210:213]
	v_mfma_f32_16x16x32_bf16 v[168:171], v[104:107], v[24:27], v[168:171]
	v_mfma_f32_16x16x32_bf16 v[210:213], v[104:107], v[60:63], v[210:213]
	s_waitcnt lgkmcnt(3)
	v_mfma_f32_16x16x32_bf16 v[168:171], v[160:163], v[92:95], v[168:171]
	v_mfma_f32_16x16x32_bf16 v[160:163], v[160:163], v[88:91], v[210:213]
	s_waitcnt lgkmcnt(2)
	v_mfma_f32_16x16x32_bf16 v[164:167], v[156:159], v[84:87], v[168:171]
	s_nop 4
	v_lshl_add_u64 v[168:169], v[186:187], 0, s[92:93]
	v_lshl_add_u64 v[168:169], v[180:181], 1, v[168:169]
	v_mfma_f32_16x16x32_bf16 v[156:159], v[156:159], v[80:83], v[160:163]
	s_nop 2
	v_add_co_u32_e32 v160, vcc, s0, v168
	s_mov_b32 s0, 0x1a100
	s_nop 0
	v_addc_co_u32_e32 v161, vcc, 0, v169, vcc
	global_store_dwordx2 v[160:161], v[172:173], off offset:1024
	v_sub_u32_e32 v160, 13, v182
	s_waitcnt lgkmcnt(1)
	v_mfma_f32_16x16x32_bf16 v[168:171], v[152:155], v[76:79], v[164:167]
	v_max_i32_e32 v160, 0, v160
	v_lshl_add_u32 v160, v160, 9, v194
	v_add3_u32 v209, v208, v232, s0
	v_mfma_f32_16x16x32_bf16 v[212:215], v[152:155], v[72:75], v[156:159]
	ds_read_b128 v[172:175], v160
	ds_read_b128 v[164:167], v209
	ds_read_b128 v[160:163], v209 offset:64
	ds_read_b128 v[152:155], v209 offset:128
	ds_read_b128 v[156:159], v209 offset:192
	s_waitcnt lgkmcnt(5)
	v_mfma_f32_16x16x32_bf16 v[176:179], v[144:147], v[64:67], v[168:171]
	v_mfma_f32_16x16x32_bf16 v[168:171], v[144:147], v[68:71], v[212:215]
	s_nop 6
	v_mul_f32_e32 v209, 0x3f3504f3, v176
	v_cmp_nlt_f32_e64 s[0:1], |v209|, 1.0
	s_and_saveexec_b64 s[8:9], s[0:1]
	s_xor_b64 s[0:1], exec, s[8:9]
	s_cbranch_execz .LBB0_685
	v_fma_f32 v144, |v209|, s20, v222
	v_fma_f32 v144, |v209|, v144, s21
	v_fma_f32 v144, |v209|, v144, s22
	v_fma_f32 v144, |v209|, v144, s23
	v_fma_f32 v144, |v209|, v144, s24
	v_fma_f32 v144, |v209|, v144, s25
	v_fma_f32 v144, |v209|, v144, |v209|
	v_mul_f32_e32 v145, 0xbfb8aa3b, v144
	v_fma_f32 v146, v144, s26, -v145
	v_rndne_f32_e32 v147, v145
	v_fmac_f32_e32 v146, 0xb2a5705f, v144
	v_sub_f32_e32 v145, v145, v147
	v_add_f32_e32 v145, v145, v146
	v_cvt_i32_f32_e32 v146, v147
	v_exp_f32_e32 v145, v145
	v_cmp_nlt_f32_e32 vcc, s27, v144
	v_ldexp_f32 v145, v145, v146
	s_nop 0
	v_cndmask_b32_e32 v145, 0, v145, vcc
	v_cmp_ngt_f32_e32 vcc, s28, v144
	s_nop 1
	v_cndmask_b32_e32 v144, v223, v145, vcc
	v_sub_f32_e32 v210, 1.0, v144

.LBB0_713:
	s_andn2_saveexec_b64 s[0:1], s[0:1]
	v_mul_f32_e32 v144, v210, v210
	v_fmamk_f32 v145, v144, 0xba1345e1, v219
	v_fmaak_f32 v145, v144, v145, 0xbcdac9b8
	v_fmaak_f32 v145, v144, v145, 0x3de703be
	v_fmaak_f32 v145, v144, v145, 0xbec09330
	v_fmaak_f32 v144, v144, v145, 0x3e0375d0
	v_fma_f32 v212, |v210|, v144, |v210|
	s_or_b64 exec, exec, s[0:1]
	v_cmp_gt_i32_e32 vcc, 14, v182
	v_bfi_b32 v209, s29, v211, v209
	v_mul_f32_e32 v170, 0.5, v170
	s_waitcnt lgkmcnt(4)
	v_cndmask_b32_e32 v147, 0, v175, vcc
	v_cndmask_b32_e32 v146, 0, v174, vcc
	v_cndmask_b32_e32 v145, 0, v173, vcc
	v_cndmask_b32_e32 v144, 0, v172, vcc
	v_add_f32_e32 v209, 1.0, v209
	v_mul_f32_e32 v209, v170, v209
	v_mfma_f32_16x16x32_bf16 v[172:175], v[144:147], v[0:3], 0
	v_bfi_b32 v170, s29, v177, v176
	v_mul_f32_e32 v168, 0.5, v168
	v_add_f32_e32 v170, 1.0, v170
	v_mfma_f32_16x16x32_bf16 v[228:231], v[144:147], v[32:35], 0
	v_mul_f32_e32 v168, v168, v170
	v_bfi_b32 v170, s29, v179, v178
	v_mul_f32_e32 v169, 0.5, v169
	v_mfma_f32_16x16x32_bf16 v[172:175], v[136:139], v[4:7], v[172:175]
	v_add_f32_e32 v170, 1.0, v170
	v_mul_f32_e32 v169, v169, v170
	v_cvt_pk_bf16_f32 v176, v168, v169
	v_mfma_f32_16x16x32_bf16 v[228:231], v[136:139], v[36:39], v[228:231]
	v_bfi_b32 v169, s29, v212, v210
	v_mul_f32_e32 v168, 0.5, v171
	v_add_f32_e32 v169, 1.0, v169
	v_mfma_f32_16x16x32_bf16 v[172:175], v[128:131], v[8:11], v[172:175]
	v_mul_f32_e32 v177, v168, v169
	v_cvt_pk_bf16_f32 v177, v209, v177
	s_mov_b32 s0, 0x1c100
	v_mfma_f32_16x16x32_bf16 v[228:231], v[128:131], v[40:43], v[228:231]
	v_add3_u32 v209, v208, v232, s0
	v_mfma_f32_16x16x32_bf16 v[172:175], v[120:123], v[12:15], v[172:175]
	v_mfma_f32_16x16x32_bf16 v[228:231], v[120:123], v[44:47], v[228:231]
	v_mfma_f32_16x16x32_bf16 v[172:175], v[112:115], v[16:19], v[172:175]
	v_mfma_f32_16x16x32_bf16 v[228:231], v[112:115], v[48:51], v[228:231]
	v_mfma_f32_16x16x32_bf16 v[172:175], v[100:103], v[20:23], v[172:175]
	v_mfma_f32_16x16x32_bf16 v[228:231], v[100:103], v[52:55], v[228:231]
	v_mfma_f32_16x16x32_bf16 v[172:175], v[96:99], v[24:27], v[172:175]
	v_mfma_f32_16x16x32_bf16 v[228:231], v[96:99], v[60:63], v[228:231]
	s_waitcnt lgkmcnt(3)
	v_mfma_f32_16x16x32_bf16 v[172:175], v[164:167], v[92:95], v[172:175]
	v_mfma_f32_16x16x32_bf16 v[164:167], v[164:167], v[88:91], v[228:231]
	s_waitcnt lgkmcnt(2)
	v_mfma_f32_16x16x32_bf16 v[168:171], v[160:163], v[84:87], v[172:175]
	s_nop 4
	v_lshl_add_u64 v[172:173], v[186:187], 0, s[92:93]
	v_lshl_add_u64 v[172:173], v[180:181], 1, v[172:173]
	v_mfma_f32_16x16x32_bf16 v[160:163], v[160:163], v[80:83], v[164:167]
	s_nop 2
	v_add_co_u32_e32 v164, vcc, s65, v172
	s_waitcnt lgkmcnt(1)
	v_mfma_f32_16x16x32_bf16 v[212:215], v[152:155], v[72:75], v[160:163]
	v_addc_co_u32_e32 v165, vcc, 0, v173, vcc
	global_store_dwordx2 v[164:165], v[176:177], off
	v_sub_u32_e32 v164, 14, v182
	v_mfma_f32_16x16x32_bf16 v[176:179], v[152:155], v[76:79], v[168:171]
	v_max_i32_e32 v164, 0, v164
	v_lshl_add_u32 v164, v164, 9, v194
	ds_read_b128 v[172:175], v164
	ds_read_b128 v[168:171], v209
	ds_read_b128 v[164:167], v209 offset:64
	ds_read_b128 v[160:163], v209 offset:128
	s_waitcnt lgkmcnt(4)
	v_mfma_f32_16x16x32_bf16 v[176:179], v[156:159], v[64:67], v[176:179]
	ds_read_b128 v[152:155], v209 offset:192
	v_mfma_f32_16x16x32_bf16 v[156:159], v[156:159], v[68:71], v[212:215]
	s_nop 5
	v_mul_f32_e32 v209, 0x3f3504f3, v176
	v_cmp_nlt_f32_e64 s[0:1], |v209|, 1.0
	s_and_saveexec_b64 s[8:9], s[0:1]
	s_xor_b64 s[0:1], exec, s[8:9]
	s_cbranch_execz .LBB0_717
	v_fma_f32 v210, |v209|, s20, v222
	v_fma_f32 v210, |v209|, v210, s21
	v_fma_f32 v210, |v209|, v210, s22
	v_fma_f32 v210, |v209|, v210, s23
	v_fma_f32 v210, |v209|, v210, s24
	v_fma_f32 v210, |v209|, v210, s25
	v_fma_f32 v210, |v209|, v210, |v209|
	v_mul_f32_e32 v211, 0xbfb8aa3b, v210
	v_fma_f32 v212, v210, s26, -v211
	v_rndne_f32_e32 v213, v211
	v_fmac_f32_e32 v212, 0xb2a5705f, v210
	v_sub_f32_e32 v211, v211, v213
	v_add_f32_e32 v211, v211, v212
	v_cvt_i32_f32_e32 v212, v213
	v_exp_f32_e32 v211, v211
	v_cmp_nlt_f32_e32 vcc, s27, v210
	v_ldexp_f32 v211, v211, v212
	s_nop 0
	v_cndmask_b32_e32 v211, 0, v211, vcc
	v_cmp_ngt_f32_e32 vcc, s28, v210
	s_nop 1
	v_cndmask_b32_e32 v210, v223, v211, vcc
	v_sub_f32_e32 v210, 1.0, v210

.LBB0_745:
	s_andn2_saveexec_b64 s[0:1], s[0:1]
	v_mul_f32_e32 v212, v210, v210
	v_fmamk_f32 v213, v212, 0xba1345e1, v219
	v_fmaak_f32 v213, v212, v213, 0xbcdac9b8
	v_fmaak_f32 v213, v212, v213, 0x3de703be
	v_fmaak_f32 v213, v212, v213, 0xbec09330
	v_fmaak_f32 v212, v212, v213, 0x3e0375d0
	v_fma_f32 v212, |v210|, v212, |v210|
	s_or_b64 exec, exec, s[0:1]
	v_cmp_gt_i32_e32 vcc, 15, v182
	s_mov_b32 s0, 0x24000
	s_waitcnt lgkmcnt(4)
	v_cndmask_b32_e32 v175, 0, v175, vcc
	v_cndmask_b32_e32 v174, 0, v174, vcc
	v_cndmask_b32_e32 v173, 0, v173, vcc
	v_cndmask_b32_e32 v172, 0, v172, vcc
	s_nop 1
	v_mfma_f32_16x16x32_bf16 v[228:231], v[172:175], v[0:3], 0
	v_mfma_f32_16x16x32_bf16 v[172:175], v[172:175], v[32:35], 0
	v_mfma_f32_16x16x32_bf16 v[228:231], v[148:151], v[4:7], v[228:231]
	v_mfma_f32_16x16x32_bf16 v[148:151], v[148:151], v[36:39], v[172:175]
	v_mfma_f32_16x16x32_bf16 v[172:175], v[140:143], v[8:11], v[228:231]
	v_mfma_f32_16x16x32_bf16 v[140:143], v[140:143], v[40:43], v[148:151]
	v_mfma_f32_16x16x32_bf16 v[148:151], v[132:135], v[12:15], v[172:175]
	v_mfma_f32_16x16x32_bf16 v[132:135], v[132:135], v[44:47], v[140:143]
	v_mfma_f32_16x16x32_bf16 v[140:143], v[124:127], v[16:19], v[148:151]
	v_mfma_f32_16x16x32_bf16 v[124:127], v[124:127], v[48:51], v[132:135]
	v_mfma_f32_16x16x32_bf16 v[132:135], v[116:119], v[20:23], v[140:143]
	v_mfma_f32_16x16x32_bf16 v[116:119], v[116:119], v[52:55], v[124:127]
	v_mfma_f32_16x16x32_bf16 v[124:127], v[108:111], v[24:27], v[132:135]
	s_nop 5
	v_bfi_b32 v133, s29, v211, v209
	v_mfma_f32_16x16x32_bf16 v[108:111], v[108:111], v[60:63], v[116:119]
	v_mul_f32_e32 v132, 0.5, v158
	s_nop 1
	v_add_f32_e32 v116, 1.0, v133
	v_mul_f32_e32 v132, v132, v116
	v_mfma_f32_16x16x32_bf16 v[116:119], v[104:107], v[28:31], v[124:127]
	v_mul_f32_e32 v133, 0.5, v156
	v_mfma_f32_16x16x32_bf16 v[104:107], v[104:107], v[56:59], v[108:111]
	s_nop 0
	v_bfi_b32 v124, s29, v177, v176
	v_add_f32_e32 v124, 1.0, v124
	v_mul_f32_e32 v125, 0.5, v157
	v_bfi_b32 v108, s29, v179, v178
	v_add_f32_e32 v126, 1.0, v108
	s_waitcnt lgkmcnt(3)
	v_mfma_f32_16x16x32_bf16 v[108:111], v[168:171], v[92:95], v[116:119]
	v_mul_f32_e32 v124, v133, v124
	v_mfma_f32_16x16x32_bf16 v[104:107], v[168:171], v[88:91], v[104:107]
	s_nop 0
	v_bfi_b32 v118, s29, v212, v210
	v_mul_f32_e32 v117, 0.5, v159
	v_add_f32_e32 v118, 1.0, v118
	v_mul_f32_e32 v117, v117, v118
	s_waitcnt lgkmcnt(2)
	v_mfma_f32_16x16x32_bf16 v[108:111], v[164:167], v[84:87], v[108:111]
	v_lshl_add_u64 v[118:119], v[186:187], 0, s[92:93]
	v_lshl_add_u64 v[118:119], v[180:181], 1, v[118:119]
	v_mul_f32_e32 v116, v125, v126
	v_mfma_f32_16x16x32_bf16 v[104:107], v[164:167], v[80:83], v[104:107]
	v_add_co_u32_e32 v118, vcc, s0, v118
	v_cvt_pk_bf16_f32 v116, v124, v116
	v_cvt_pk_bf16_f32 v117, v132, v117
	v_addc_co_u32_e32 v119, vcc, 0, v119, vcc
	global_store_dwordx2 v[118:119], v[116:117], off offset:3072
	v_sub_u32_e32 v116, 15, v182
	s_waitcnt lgkmcnt(1)
	v_mfma_f32_16x16x32_bf16 v[140:143], v[160:163], v[76:79], v[108:111]
	s_mov_b32 s0, 0x1e100
	v_add3_u32 v156, v208, v232, s0
	s_nop 0
	v_max_i32_e32 v108, 0, v116
	v_lshl_add_u32 v108, v108, 9, v194
	v_mfma_f32_16x16x32_bf16 v[158:161], v[160:163], v[72:75], v[104:107]
	ds_read_b128 v[132:135], v108
	ds_read_b128 v[124:127], v156
	ds_read_b128 v[116:119], v156 offset:64
	ds_read_b128 v[108:111], v156 offset:128
	ds_read_b128 v[104:107], v156 offset:192
	s_waitcnt lgkmcnt(5)
	v_mfma_f32_16x16x32_bf16 v[148:151], v[152:155], v[64:67], v[140:143]
	v_mfma_f32_16x16x32_bf16 v[140:143], v[152:155], v[68:71], v[158:161]
	s_nop 6
	v_mul_f32_e32 v156, 0x3f3504f3, v148
	v_cmp_nlt_f32_e64 s[0:1], |v156|, 1.0
	s_and_saveexec_b64 s[8:9], s[0:1]
	s_xor_b64 s[0:1], exec, s[8:9]
	s_cbranch_execz .LBB0_749
	v_fma_f32 v152, |v156|, s20, v222
	v_fma_f32 v152, |v156|, v152, s21
	v_fma_f32 v152, |v156|, v152, s22
	v_fma_f32 v152, |v156|, v152, s23
	v_fma_f32 v152, |v156|, v152, s24
	v_fma_f32 v152, |v156|, v152, s25
	v_fma_f32 v152, |v156|, v152, |v156|
	v_mul_f32_e32 v153, 0xbfb8aa3b, v152
	v_fma_f32 v154, v152, s26, -v153
	v_rndne_f32_e32 v155, v153
	v_fmac_f32_e32 v154, 0xb2a5705f, v152
	v_sub_f32_e32 v153, v153, v155
	v_add_f32_e32 v153, v153, v154
	v_cvt_i32_f32_e32 v154, v155
	v_exp_f32_e32 v153, v153
	v_cmp_nlt_f32_e32 vcc, s27, v152
	v_ldexp_f32 v153, v153, v154
	s_nop 0
	v_cndmask_b32_e32 v153, 0, v153, vcc
	v_cmp_ngt_f32_e32 vcc, s28, v152
	s_nop 1
	v_cndmask_b32_e32 v152, v223, v153, vcc
	v_sub_f32_e32 v157, 1.0, v152
